# attention: second key-half K fragment reads issued in the first half's exp block (LDS latency hidden under softmax VALU and PV MFMAs)
# baseline (speedup 1.0000x reference)
; __device__ __forceinline__ unsigned cvt_pk_bf16(float lo, float hi) { const f32x2c_ v = {lo, hi}; const bf16x2c_ b = __builtin_convertvector(v, bf16x2c_); return __builtin_bit_cast(unsigned, b); }
; #define LAS __attribute__((address_space(3)))
; #define MFMA32(a, b, c) __builtin_amdgcn_mfma_f32_32x32x16_bf16(a, b, c, 0, 0, 0)
; __device__ __forceinline__ void attn_unit(int bh, int qb, const bf16_t* QKV, const bf16_t* KF, const float* cstab, const float* qg, bf16_t* MIX, LAS unsigned char* lds) {
;     ...
;             const LAS unsigned char* kp = buf + (32 * kb + r32) * KROW + 16 * hi;
;             f32x16 p = negm;
;             bf16x8 kfr[6];
; #pragma unroll
;             for (int d0 = 0; d0 < 6; ++d0) kfr[d0] = *(const LAS bf16x8*)(kp + 32 * d0);
;             __builtin_amdgcn_s_setprio(1);
; #pragma unroll
;             for (int d0 = 0; d0 < 6; ++d0) p = MFMA32(kfr[d0], qf[d0], p);
;     ...
;             float ps = 0.f;
; #pragma unroll
;             for (int r = 0; r < 16; ++r) { p[r] = __builtin_amdgcn_exp2f(p[r]); ps += p[r]; }
;             lrun += ps;
;             u32x4 w0, w1;
; #pragma unroll
;             for (int k = 0; k < 4; ++k) { w0[k] = cvt_pk_bf16(p[2 * k], p[2 * k + 1]); w1[k] = cvt_pk_bf16(p[8 + 2 * k], p[8 + 2 * k + 1]); }
;             const bf16x8 pb0 = __builtin_bit_cast(bf16x8, w0), pb1 = __builtin_bit_cast(bf16x8, w1);
;             const LAS unsigned char* vp = buf + vtb + (32 * kb) * VROW;
; #pragma unroll
;             for (int db = 0; db < 2; ++db) {
;                 const v4i16_t a0 = __builtin_amdgcn_ds_read_tr16_b64_v4i16((LAS v4i16_t*)(vp + db * 64));
;                 const v4i16_t a1 = __builtin_amdgcn_ds_read_tr16_b64_v4i16((LAS v4i16_t*)(vp + db * 64 + 8 * VROW));
;                 const v4i16_t c0 = __builtin_amdgcn_ds_read_tr16_b64_v4i16((LAS v4i16_t*)(vp + db * 64 + 16 * VROW));
;                 const v4i16_t c1 = __builtin_amdgcn_ds_read_tr16_b64_v4i16((LAS v4i16_t*)(vp + db * 64 + 24 * VROW));
;                 const bf16x8 va = {a0[0], a0[1], a0[2], a0[3], a1[0], a1[1], a1[2], a1[3]}, vc = {c0[0], c0[1], c0[2], c0[3], c1[0], c1[1], c1[2], c1[3]};
;                 __builtin_amdgcn_s_setprio(1);
;                 if (db == 0) { o0 = MFMA32(va, pb0, o0); o0 = MFMA32(vc, pb1, o0); }
;                 else { o1 = MFMA32(va, pb0, o1); o1 = MFMA32(vc, pb1, o1); }
;                 __builtin_amdgcn_s_setprio(0);
;             }
.LBB0_1066:
	v_add_u32_e32 v172, v119, v115
	ds_read_b64_tr_b16 v[156:157], v172 offset:13312
	ds_read_b64_tr_b16 v[158:159], v172 offset:14848
	ds_read_b64_tr_b16 v[160:161], v172 offset:16384
	ds_read_b64_tr_b16 v[162:163], v172 offset:17920
	ds_read_b64_tr_b16 v[164:165], v172 offset:13376
	ds_read_b64_tr_b16 v[166:167], v172 offset:14912
	ds_read_b64_tr_b16 v[168:169], v172 offset:16448
	ds_read_b64_tr_b16 v[170:171], v172 offset:17984
	ds_read_b128 v[202:205], v120 offset:6656
	ds_read_b128 v[206:209], v120 offset:6688
	ds_read_b128 v[210:213], v120 offset:6720
	ds_read_b128 v[214:217], v120 offset:6752
	ds_read_b128 v[218:221], v120 offset:6784
	ds_read_b128 v[222:225], v120 offset:6816
	v_exp_f32_e32 v48, v48
	v_exp_f32_e32 v49, v49
	v_exp_f32_e32 v50, v50
	v_exp_f32_e32 v51, v51
	v_exp_f32_e32 v122, v52
	v_add_f32_e32 v121, v49, v48
	v_add_f32_e32 v121, v50, v121
	v_add_f32_e32 v121, v51, v121
	v_add_f32_e32 v52, v122, v121
	v_exp_f32_e32 v121, v53
	v_exp_f32_e32 v123, v54
	v_exp_f32_e32 v55, v55
	v_exp_f32_e32 v53, v56
	v_add_f32_e32 v52, v121, v52
	v_exp_f32_e32 v54, v57
	v_add_f32_e32 v52, v123, v52
	v_exp_f32_e32 v56, v58
	v_add_f32_e32 v52, v55, v52
	v_exp_f32_e32 v57, v59
	v_add_f32_e32 v52, v53, v52
	v_exp_f32_e32 v58, v60
	v_add_f32_e32 v52, v54, v52
	v_exp_f32_e32 v59, v61
	v_add_f32_e32 v52, v56, v52
	v_exp_f32_e32 v60, v62
	v_add_f32_e32 v52, v57, v52
	v_exp_f32_e32 v61, v63
	v_add_f32_e32 v52, v58, v52
	v_add_f32_e32 v52, v59, v52
	v_add_f32_e32 v52, v60, v52
	v_cvt_pk_bf16_f32 v48, v48, v49
	v_cvt_pk_bf16_f32 v49, v50, v51
	v_cvt_pk_bf16_f32 v50, v122, v121
	v_add_f32_e32 v124, v61, v52
	v_cvt_pk_bf16_f32 v52, v53, v54
	v_cvt_pk_bf16_f32 v53, v56, v57
	v_cvt_pk_bf16_f32 v54, v58, v59
	v_cvt_pk_bf16_f32 v51, v123, v55
	v_cvt_pk_bf16_f32 v55, v60, v61
	s_setprio 1
	s_waitcnt lgkmcnt(12)
	v_mfma_f32_32x32x16_bf16 v[0:15], v[156:159], v[48:51], v[0:15]
	s_waitcnt lgkmcnt(10)
	v_mfma_f32_32x32x16_bf16 v[0:15], v[160:163], v[52:55], v[0:15]
	s_setprio 0
	s_setprio 1
	s_waitcnt lgkmcnt(8)
	v_mfma_f32_32x32x16_bf16 v[16:31], v[164:167], v[48:51], v[16:31]
	s_waitcnt lgkmcnt(6)
	v_mfma_f32_32x32x16_bf16 v[16:31], v[168:171], v[52:55], v[16:31]
	s_setprio 0
	v_add_f32_e32 v107, v107, v124
	s_add_i32 s44, s43, 0x60
	s_cmp_gt_i32 s44, s2
	s_cbranch_scc0 .LBB0_1069

; #define LAS __attribute__((address_space(3)))
; #define MFMA32(a, b, c) __builtin_amdgcn_mfma_f32_32x32x16_bf16(a, b, c, 0, 0, 0)
; __device__ __forceinline__ void attn_unit(int bh, int qb, const bf16_t* QKV, const bf16_t* KF, const float* cstab, const float* qg, bf16_t* MIX, LAS unsigned char* lds) {
;     ...
;             if (key0 > qw + 31) continue;
;             const LAS unsigned char* kp = buf + (32 * kb + r32) * KROW + 16 * hi;
;             f32x16 p = negm;
;             bf16x8 kfr[6];
; #pragma unroll
;             for (int d0 = 0; d0 < 6; ++d0) kfr[d0] = *(const LAS bf16x8*)(kp + 32 * d0);
;             __builtin_amdgcn_s_setprio(1);
; #pragma unroll
;             for (int d0 = 0; d0 < 6; ++d0) p = MFMA32(kfr[d0], qf[d0], p);
;             __builtin_amdgcn_s_setprio(0);
;             if (key0 + 31 > qw) {
; #pragma unroll
;                 for (int r = 0; r < 16; ++r) { const int key = key0 + (r & 3) + 8 * (r >> 2) + 4 * hi; if (key > q) p[r] = -1e30f; }
.LBB0_1068:
	s_add_i32 s44, s43, 0x60
	s_cmp_gt_i32 s44, s2
	s_cbranch_scc1 .LBB0_1067
	ds_read_b128 v[202:205], v120 offset:6656
	ds_read_b128 v[206:209], v120 offset:6688
	ds_read_b128 v[210:213], v120 offset:6720
	ds_read_b128 v[214:217], v120 offset:6752
	ds_read_b128 v[218:221], v120 offset:6784
	ds_read_b128 v[222:225], v120 offset:6816
.LBB0_1069:
	s_setprio 1
	s_waitcnt lgkmcnt(5)
	v_mfma_f32_32x32x16_bf16 v[48:63], v[202:205], v[74:77], v[32:47]
	s_waitcnt lgkmcnt(4)
	v_mfma_f32_32x32x16_bf16 v[48:63], v[206:209], v[78:81], v[48:63]
	s_waitcnt lgkmcnt(3)
	v_mfma_f32_32x32x16_bf16 v[48:63], v[210:213], v[82:85], v[48:63]
	s_waitcnt lgkmcnt(2)
	v_mfma_f32_32x32x16_bf16 v[48:63], v[214:217], v[90:93], v[48:63]
	s_waitcnt lgkmcnt(1)
	v_mfma_f32_32x32x16_bf16 v[48:63], v[218:221], v[94:97], v[48:63]
	s_waitcnt lgkmcnt(0)
	v_mfma_f32_32x32x16_bf16 v[48:63], v[222:225], v[98:101], v[48:63]
	s_setprio 0
	s_add_i32 s44, s43, 0x7f
	s_cmp_le_i32 s44, s37
	s_cbranch_scc1 .LBB0_1071
	v_add_u32_e32 v120, s43, v105
	v_add_u32_e32 v121, 0x60, v120
	v_cmp_lt_i32_e32 vcc, v121, v139
	s_nop 4
	v_cndmask_b32_e32 v49, v239, v49, vcc
	v_cmp_le_i32_e32 vcc, v121, v139
	v_add_u32_e32 v121, 0x62, v120
	s_nop 0
	v_cndmask_b32_e32 v48, v239, v48, vcc
	v_cmp_le_i32_e32 vcc, v121, v139
	v_add_u32_e32 v121, 0x63, v120
	s_nop 0
	v_cndmask_b32_e32 v50, v239, v50, vcc
	v_cmp_le_i32_e32 vcc, v121, v139
	v_add_u32_e32 v121, 0x68, v120
	s_nop 0
	v_cndmask_b32_e32 v51, v239, v51, vcc
	v_cmp_le_i32_e32 vcc, v121, v139
	v_add_u32_e32 v121, 0x69, v120
	s_nop 0
	v_cndmask_b32_e32 v52, v239, v52, vcc
	v_cmp_le_i32_e32 vcc, v121, v139
	v_add_u32_e32 v121, 0x6a, v120
	s_nop 0
	v_cndmask_b32_e32 v53, v239, v53, vcc
	v_cmp_le_i32_e32 vcc, v121, v139
	v_add_u32_e32 v121, 0x6b, v120
	s_nop 0
	v_cndmask_b32_e32 v54, v239, v54, vcc
	v_cmp_le_i32_e32 vcc, v121, v139
	v_add_u32_e32 v121, 0x70, v120
	s_nop 0
	v_cndmask_b32_e32 v55, v239, v55, vcc
	v_cmp_le_i32_e32 vcc, v121, v139
	v_add_u32_e32 v121, 0x71, v120
	s_nop 0
	v_cndmask_b32_e32 v56, v239, v56, vcc
	v_cmp_le_i32_e32 vcc, v121, v139
	v_add_u32_e32 v121, 0x72, v120
	s_nop 0
	v_cndmask_b32_e32 v57, v239, v57, vcc
	v_cmp_le_i32_e32 vcc, v121, v139
	v_add_u32_e32 v121, 0x73, v120
	s_nop 0
	v_cndmask_b32_e32 v58, v239, v58, vcc
	v_cmp_le_i32_e32 vcc, v121, v139
	v_add_u32_e32 v121, 0x78, v120
	s_nop 0
	v_cndmask_b32_e32 v59, v239, v59, vcc
	v_cmp_le_i32_e32 vcc, v121, v139
	v_add_u32_e32 v121, 0x79, v120
	s_nop 0
	v_cndmask_b32_e32 v60, v239, v60, vcc
	v_cmp_le_i32_e32 vcc, v121, v139
	v_add_u32_e32 v121, 0x7a, v120
	v_add_u32_e32 v120, 0x7b, v120
	v_cndmask_b32_e32 v61, v239, v61, vcc
	v_cmp_le_i32_e32 vcc, v121, v139
	s_nop 1
	v_cndmask_b32_e32 v62, v239, v62, vcc
	v_cmp_le_i32_e32 vcc, v120, v139
	s_nop 1
	v_cndmask_b32_e32 v63, v239, v63, vcc

; __device__ __forceinline__ unsigned cvt_pk_bf16(float lo, float hi) { const f32x2c_ v = {lo, hi}; const bf16x2c_ b = __builtin_convertvector(v, bf16x2c_); return __builtin_bit_cast(unsigned, b); }
; #define LAS __attribute__((address_space(3)))
; #define MFMA32(a, b, c) __builtin_amdgcn_mfma_f32_32x32x16_bf16(a, b, c, 0, 0, 0)
; __device__ __forceinline__ void attn_unit(int bh, int qb, const bf16_t* QKV, const bf16_t* KF, const float* cstab, const float* qg, bf16_t* MIX, LAS unsigned char* lds) {
;     ...
;             const LAS unsigned char* kp = buf + (32 * kb + r32) * KROW + 16 * hi;
;             f32x16 p = negm;
;             bf16x8 kfr[6];
; #pragma unroll
;             for (int d0 = 0; d0 < 6; ++d0) kfr[d0] = *(const LAS bf16x8*)(kp + 32 * d0);
;             __builtin_amdgcn_s_setprio(1);
; #pragma unroll
;             for (int d0 = 0; d0 < 6; ++d0) p = MFMA32(kfr[d0], qf[d0], p);
;     ...
;             float ps = 0.f;
; #pragma unroll
;             for (int r = 0; r < 16; ++r) { p[r] = __builtin_amdgcn_exp2f(p[r]); ps += p[r]; }
;             lrun += ps;
;             u32x4 w0, w1;
; #pragma unroll
;             for (int k = 0; k < 4; ++k) { w0[k] = cvt_pk_bf16(p[2 * k], p[2 * k + 1]); w1[k] = cvt_pk_bf16(p[8 + 2 * k], p[8 + 2 * k + 1]); }
;             const bf16x8 pb0 = __builtin_bit_cast(bf16x8, w0), pb1 = __builtin_bit_cast(bf16x8, w1);
;             const LAS unsigned char* vp = buf + vtb + (32 * kb) * VROW;
; #pragma unroll
;             for (int db = 0; db < 2; ++db) {
;                 const v4i16_t a0 = __builtin_amdgcn_ds_read_tr16_b64_v4i16((LAS v4i16_t*)(vp + db * 64));
;                 const v4i16_t a1 = __builtin_amdgcn_ds_read_tr16_b64_v4i16((LAS v4i16_t*)(vp + db * 64 + 8 * VROW));
;                 const v4i16_t c0 = __builtin_amdgcn_ds_read_tr16_b64_v4i16((LAS v4i16_t*)(vp + db * 64 + 16 * VROW));
;                 const v4i16_t c1 = __builtin_amdgcn_ds_read_tr16_b64_v4i16((LAS v4i16_t*)(vp + db * 64 + 24 * VROW));
;                 const bf16x8 va = {a0[0], a0[1], a0[2], a0[3], a1[0], a1[1], a1[2], a1[3]}, vc = {c0[0], c0[1], c0[2], c0[3], c1[0], c1[1], c1[2], c1[3]};
;                 __builtin_amdgcn_s_setprio(1);
;                 if (db == 0) { o0 = MFMA32(va, pb0, o0); o0 = MFMA32(vc, pb1, o0); }
;                 else { o1 = MFMA32(va, pb0, o1); o1 = MFMA32(vc, pb1, o1); }
;                 __builtin_amdgcn_s_setprio(0);
;             }
.LBB0_1107:
	v_add_u32_e32 v172, v119, v115
	ds_read_b64_tr_b16 v[156:157], v172 offset:13312
	ds_read_b64_tr_b16 v[158:159], v172 offset:14848
	ds_read_b64_tr_b16 v[160:161], v172 offset:16384
	ds_read_b64_tr_b16 v[162:163], v172 offset:17920
	ds_read_b64_tr_b16 v[164:165], v172 offset:13376
	ds_read_b64_tr_b16 v[166:167], v172 offset:14912
	ds_read_b64_tr_b16 v[168:169], v172 offset:16448
	ds_read_b64_tr_b16 v[170:171], v172 offset:17984
	ds_read_b128 v[202:205], v120 offset:6656
	ds_read_b128 v[206:209], v120 offset:6688
	ds_read_b128 v[210:213], v120 offset:6720
	ds_read_b128 v[214:217], v120 offset:6752
	ds_read_b128 v[218:221], v120 offset:6784
	ds_read_b128 v[222:225], v120 offset:6816
	v_exp_f32_e32 v48, v48
	v_exp_f32_e32 v49, v49
	v_exp_f32_e32 v50, v50
	v_exp_f32_e32 v51, v51
	v_exp_f32_e32 v122, v52
	v_add_f32_e32 v121, v49, v48
	v_add_f32_e32 v121, v50, v121
	v_add_f32_e32 v121, v51, v121
	v_add_f32_e32 v52, v122, v121
	v_exp_f32_e32 v121, v53
	v_exp_f32_e32 v123, v54
	v_exp_f32_e32 v55, v55
	v_exp_f32_e32 v53, v56
	v_add_f32_e32 v52, v121, v52
	v_exp_f32_e32 v54, v57
	v_add_f32_e32 v52, v123, v52
	v_exp_f32_e32 v56, v58
	v_add_f32_e32 v52, v55, v52
	v_exp_f32_e32 v57, v59
	v_add_f32_e32 v52, v53, v52
	v_exp_f32_e32 v58, v60
	v_add_f32_e32 v52, v54, v52
	v_exp_f32_e32 v59, v61
	v_add_f32_e32 v52, v56, v52
	v_exp_f32_e32 v60, v62
	v_add_f32_e32 v52, v57, v52
	v_exp_f32_e32 v61, v63
	v_add_f32_e32 v52, v58, v52
	v_add_f32_e32 v52, v59, v52
	v_add_f32_e32 v52, v60, v52
	v_cvt_pk_bf16_f32 v48, v48, v49
	v_cvt_pk_bf16_f32 v49, v50, v51
	v_cvt_pk_bf16_f32 v50, v122, v121
	v_add_f32_e32 v124, v61, v52
	v_cvt_pk_bf16_f32 v52, v53, v54
	v_cvt_pk_bf16_f32 v53, v56, v57
	v_cvt_pk_bf16_f32 v54, v58, v59
	v_cvt_pk_bf16_f32 v51, v123, v55
	v_cvt_pk_bf16_f32 v55, v60, v61
	s_setprio 1
	s_waitcnt lgkmcnt(12)
	v_mfma_f32_32x32x16_bf16 v[0:15], v[156:159], v[48:51], v[0:15]
	s_waitcnt lgkmcnt(10)
	v_mfma_f32_32x32x16_bf16 v[0:15], v[160:163], v[52:55], v[0:15]
	s_setprio 0
	s_setprio 1
	s_waitcnt lgkmcnt(8)
	v_mfma_f32_32x32x16_bf16 v[16:31], v[164:167], v[48:51], v[16:31]
	s_waitcnt lgkmcnt(6)
	v_mfma_f32_32x32x16_bf16 v[16:31], v[168:171], v[52:55], v[16:31]
	s_setprio 0
	v_add_f32_e32 v107, v107, v124
	s_add_i32 s30, s29, 0x60
	s_cmp_gt_i32 s30, s18
	s_cbranch_scc0 .LBB0_1110

; #define LAS __attribute__((address_space(3)))
; #define MFMA32(a, b, c) __builtin_amdgcn_mfma_f32_32x32x16_bf16(a, b, c, 0, 0, 0)
; __device__ __forceinline__ void attn_unit(int bh, int qb, const bf16_t* QKV, const bf16_t* KF, const float* cstab, const float* qg, bf16_t* MIX, LAS unsigned char* lds) {
;     ...
;             if (key0 > qw + 31) continue;
;             const LAS unsigned char* kp = buf + (32 * kb + r32) * KROW + 16 * hi;
;             f32x16 p = negm;
;             bf16x8 kfr[6];
; #pragma unroll
;             for (int d0 = 0; d0 < 6; ++d0) kfr[d0] = *(const LAS bf16x8*)(kp + 32 * d0);
;             __builtin_amdgcn_s_setprio(1);
; #pragma unroll
;             for (int d0 = 0; d0 < 6; ++d0) p = MFMA32(kfr[d0], qf[d0], p);
;             __builtin_amdgcn_s_setprio(0);
;             if (key0 + 31 > qw) {
; #pragma unroll
;                 for (int r = 0; r < 16; ++r) { const int key = key0 + (r & 3) + 8 * (r >> 2) + 4 * hi; if (key > q) p[r] = -1e30f; }
.LBB0_1109:
	s_add_i32 s30, s29, 0x60
	s_cmp_gt_i32 s30, s18
	s_cbranch_scc1 .LBB0_1108
	ds_read_b128 v[202:205], v120 offset:6656
	ds_read_b128 v[206:209], v120 offset:6688
	ds_read_b128 v[210:213], v120 offset:6720
	ds_read_b128 v[214:217], v120 offset:6752
	ds_read_b128 v[218:221], v120 offset:6784
	ds_read_b128 v[222:225], v120 offset:6816
.LBB0_1110:
	s_setprio 1
	s_waitcnt lgkmcnt(5)
	v_mfma_f32_32x32x16_bf16 v[48:63], v[202:205], v[74:77], v[32:47]
	s_waitcnt lgkmcnt(4)
	v_mfma_f32_32x32x16_bf16 v[48:63], v[206:209], v[78:81], v[48:63]
	s_waitcnt lgkmcnt(3)
	v_mfma_f32_32x32x16_bf16 v[48:63], v[210:213], v[82:85], v[48:63]
	s_waitcnt lgkmcnt(2)
	v_mfma_f32_32x32x16_bf16 v[48:63], v[214:217], v[90:93], v[48:63]
	s_waitcnt lgkmcnt(1)
	v_mfma_f32_32x32x16_bf16 v[48:63], v[218:221], v[94:97], v[48:63]
	s_waitcnt lgkmcnt(0)
	v_mfma_f32_32x32x16_bf16 v[48:63], v[222:225], v[98:101], v[48:63]
	s_setprio 0
	s_add_i32 s30, s29, 0x7f
	s_cmp_le_i32 s30, s22
	s_cbranch_scc1 .LBB0_1112
	v_add_u32_e32 v120, s29, v105
	v_add_u32_e32 v121, 0x60, v120
	v_cmp_lt_i32_e32 vcc, v121, v139
	s_nop 4
	v_cndmask_b32_e32 v49, v239, v49, vcc
	v_cmp_le_i32_e32 vcc, v121, v139
	v_add_u32_e32 v121, 0x62, v120
	s_nop 0
	v_cndmask_b32_e32 v48, v239, v48, vcc
	v_cmp_le_i32_e32 vcc, v121, v139
	v_add_u32_e32 v121, 0x63, v120
	s_nop 0
	v_cndmask_b32_e32 v50, v239, v50, vcc
	v_cmp_le_i32_e32 vcc, v121, v139
	v_add_u32_e32 v121, 0x68, v120
	s_nop 0
	v_cndmask_b32_e32 v51, v239, v51, vcc
	v_cmp_le_i32_e32 vcc, v121, v139
	v_add_u32_e32 v121, 0x69, v120
	s_nop 0
	v_cndmask_b32_e32 v52, v239, v52, vcc
	v_cmp_le_i32_e32 vcc, v121, v139
	v_add_u32_e32 v121, 0x6a, v120
	s_nop 0
	v_cndmask_b32_e32 v53, v239, v53, vcc
	v_cmp_le_i32_e32 vcc, v121, v139
	v_add_u32_e32 v121, 0x6b, v120
	s_nop 0
	v_cndmask_b32_e32 v54, v239, v54, vcc
	v_cmp_le_i32_e32 vcc, v121, v139
	v_add_u32_e32 v121, 0x70, v120
	s_nop 0
	v_cndmask_b32_e32 v55, v239, v55, vcc
	v_cmp_le_i32_e32 vcc, v121, v139
	v_add_u32_e32 v121, 0x71, v120
	s_nop 0
	v_cndmask_b32_e32 v56, v239, v56, vcc
	v_cmp_le_i32_e32 vcc, v121, v139
	v_add_u32_e32 v121, 0x72, v120
	s_nop 0
	v_cndmask_b32_e32 v57, v239, v57, vcc
	v_cmp_le_i32_e32 vcc, v121, v139
	v_add_u32_e32 v121, 0x73, v120
	s_nop 0
	v_cndmask_b32_e32 v58, v239, v58, vcc
	v_cmp_le_i32_e32 vcc, v121, v139
	v_add_u32_e32 v121, 0x78, v120
	s_nop 0
	v_cndmask_b32_e32 v59, v239, v59, vcc
	v_cmp_le_i32_e32 vcc, v121, v139
	v_add_u32_e32 v121, 0x79, v120
	s_nop 0
	v_cndmask_b32_e32 v60, v239, v60, vcc
	v_cmp_le_i32_e32 vcc, v121, v139
	v_add_u32_e32 v121, 0x7a, v120
	v_add_u32_e32 v120, 0x7b, v120
	v_cndmask_b32_e32 v61, v239, v61, vcc
	v_cmp_le_i32_e32 vcc, v121, v139
	s_nop 1
	v_cndmask_b32_e32 v62, v239, v62, vcc
	v_cmp_le_i32_e32 vcc, v120, v139
	s_nop 1
	v_cndmask_b32_e32 v63, v239, v63, vcc
